# rope cos/sin loads batched per 8 rows in EpiAbIn epilogue
# speedup vs baseline: 1.0935x; 1.0113x over previous
.LBB0_883:
	s_cmp_lg_u64 s[42:43], 0
	s_cbranch_scc1 .Lrope_nopf
	global_load_dwordx2 v[232:233], v[6:7], off offset:-512
	global_load_dwordx2 v[234:235], v[6:7], off offset:-384
	global_load_dwordx2 v[236:237], v[6:7], off offset:-256
	global_load_dwordx2 v[238:239], v[6:7], off offset:-128
	global_load_dwordx2 v[240:241], v[6:7], off
	global_load_dwordx2 v[242:243], v[6:7], off offset:128
	global_load_dwordx2 v[244:245], v[6:7], off offset:256
	global_load_dwordx2 v[246:247], v[6:7], off offset:384
	s_waitcnt vmcnt(0)
.Lrope_nopf:
	ds_read_b32 v8, v12
	s_and_saveexec_b64 s[24:25], s[42:43]
	s_xor_b64 s[24:25], exec, s[24:25]
	s_lshl_b32 s30, s28, 5
	s_or_saveexec_b64 s[24:25], s[24:25]
	v_mov_b64_e32 v[10:11], s[30:31]
	s_xor_b64 exec, exec, s[24:25]
	s_cbranch_execz .LBB0_887
	v_mov_b64_e32 v[10:11], v[232:233]
	ds_read_b32 v9, v0
	s_add_u32 s26, s22, 0xffffff20
	s_addc_u32 s27, s23, -1
	s_waitcnt lgkmcnt(0)
	v_cndmask_b32_e64 v9, v9, -v9, s[40:41]
	v_pk_mul_f32 v[8:9], v[8:9], v[10:11]
	s_nop 0
	v_add_f32_e32 v8, v8, v9
	v_mov_b64_e32 v[10:11], s[26:27]

.LBB0_889:
	s_or_b64 exec, exec, s[24:25]
	ds_read_b32 v8, v12 offset:260
	s_and_saveexec_b64 s[24:25], s[42:43]
	s_xor_b64 s[24:25], exec, s[24:25]
	s_add_u32 s26, s22, 0xffffff40
	s_addc_u32 s27, s23, -1
	s_or_saveexec_b64 s[24:25], s[24:25]
	v_mov_b64_e32 v[10:11], s[26:27]
	s_xor_b64 exec, exec, s[24:25]
	s_cbranch_execz .LBB0_893
	v_mov_b64_e32 v[10:11], v[234:235]
	ds_read_b32 v9, v0 offset:260
	s_lshl_b32 s26, s28, 5
	s_or_b32 s30, s26, 32
	s_waitcnt lgkmcnt(0)
	v_cndmask_b32_e64 v9, v9, -v9, s[40:41]
	v_pk_mul_f32 v[8:9], v[8:9], v[10:11]
	s_nop 0
	v_add_f32_e32 v8, v8, v9
	v_mov_b64_e32 v[10:11], s[30:31]

.LBB0_895:
	s_or_b64 exec, exec, s[24:25]
	ds_read_b32 v8, v12 offset:520
	s_and_saveexec_b64 s[24:25], s[42:43]
	s_xor_b64 s[24:25], exec, s[24:25]
	s_add_u32 s26, s22, 0xffffff60
	s_addc_u32 s27, s23, -1
	s_or_saveexec_b64 s[24:25], s[24:25]
	v_mov_b64_e32 v[10:11], s[26:27]
	s_xor_b64 exec, exec, s[24:25]
	s_cbranch_execz .LBB0_899
	v_mov_b64_e32 v[10:11], v[236:237]
	ds_read_b32 v9, v0 offset:520
	s_lshl_b32 s26, s28, 5
	s_or_b32 s30, s26, 64
	s_waitcnt lgkmcnt(0)
	v_cndmask_b32_e64 v9, v9, -v9, s[40:41]
	v_pk_mul_f32 v[8:9], v[8:9], v[10:11]
	s_nop 0
	v_add_f32_e32 v8, v8, v9
	v_mov_b64_e32 v[10:11], s[30:31]

.LBB0_901:
	s_or_b64 exec, exec, s[24:25]
	ds_read_b32 v8, v12 offset:780
	s_and_saveexec_b64 s[24:25], s[42:43]
	s_xor_b64 s[24:25], exec, s[24:25]
	s_add_u32 s26, s22, 0xffffff80
	s_addc_u32 s27, s23, -1
	s_or_saveexec_b64 s[24:25], s[24:25]
	v_mov_b64_e32 v[10:11], s[26:27]
	s_xor_b64 exec, exec, s[24:25]
	s_cbranch_execz .LBB0_905
	v_mov_b64_e32 v[10:11], v[238:239]
	ds_read_b32 v9, v0 offset:780
	s_lshl_b32 s26, s28, 5
	s_or_b32 s30, s26, 0x60
	s_waitcnt lgkmcnt(0)
	v_cndmask_b32_e64 v9, v9, -v9, s[40:41]
	v_pk_mul_f32 v[8:9], v[8:9], v[10:11]
	s_nop 0
	v_add_f32_e32 v8, v8, v9
	v_mov_b64_e32 v[10:11], s[30:31]

.LBB0_907:
	s_or_b64 exec, exec, s[24:25]
	ds_read_b32 v8, v12 offset:1040
	s_and_saveexec_b64 s[24:25], s[42:43]
	s_xor_b64 s[24:25], exec, s[24:25]
	s_add_u32 s26, s22, 0xffffffa0
	s_addc_u32 s27, s23, -1
	s_or_saveexec_b64 s[24:25], s[24:25]
	v_mov_b64_e32 v[10:11], s[26:27]
	s_xor_b64 exec, exec, s[24:25]
	s_cbranch_execz .LBB0_911
	v_mov_b64_e32 v[10:11], v[240:241]
	ds_read_b32 v9, v0 offset:1040
	s_lshl_b32 s26, s28, 5
	s_or_b32 s30, s26, 0x80
	s_waitcnt lgkmcnt(0)
	v_cndmask_b32_e64 v9, v9, -v9, s[40:41]
	v_pk_mul_f32 v[8:9], v[8:9], v[10:11]
	s_nop 0
	v_add_f32_e32 v8, v8, v9
	v_mov_b64_e32 v[10:11], s[30:31]

.LBB0_913:
	s_or_b64 exec, exec, s[24:25]
	ds_read_b32 v8, v12 offset:1300
	s_and_saveexec_b64 s[24:25], s[42:43]
	s_xor_b64 s[24:25], exec, s[24:25]
	s_add_u32 s26, s22, 0xffffffc0
	s_addc_u32 s27, s23, -1
	s_or_saveexec_b64 s[24:25], s[24:25]
	v_mov_b64_e32 v[10:11], s[26:27]
	s_xor_b64 exec, exec, s[24:25]
	s_cbranch_execz .LBB0_917
	v_mov_b64_e32 v[10:11], v[242:243]
	ds_read_b32 v9, v0 offset:1300
	s_lshl_b32 s26, s28, 5
	s_or_b32 s30, s26, 0xa0
	s_waitcnt lgkmcnt(0)
	v_cndmask_b32_e64 v9, v9, -v9, s[40:41]
	v_pk_mul_f32 v[8:9], v[8:9], v[10:11]
	s_nop 0
	v_add_f32_e32 v8, v8, v9
	v_mov_b64_e32 v[10:11], s[30:31]

.LBB0_919:
	s_or_b64 exec, exec, s[24:25]
	ds_read_b32 v8, v12 offset:1560
	s_and_saveexec_b64 s[24:25], s[42:43]
	s_xor_b64 s[24:25], exec, s[24:25]
	s_add_u32 s26, s22, 0xffffffe0
	s_addc_u32 s27, s23, -1
	s_or_saveexec_b64 s[24:25], s[24:25]
	v_mov_b64_e32 v[10:11], s[26:27]
	s_xor_b64 exec, exec, s[24:25]
	s_cbranch_execz .LBB0_923
	v_mov_b64_e32 v[10:11], v[244:245]
	ds_read_b32 v9, v0 offset:1560
	s_lshl_b32 s26, s28, 5
	s_or_b32 s30, s26, 0xc0
	s_waitcnt lgkmcnt(0)
	v_cndmask_b32_e64 v9, v9, -v9, s[40:41]
	v_pk_mul_f32 v[8:9], v[8:9], v[10:11]
	s_nop 0
	v_add_f32_e32 v8, v8, v9
	v_mov_b64_e32 v[10:11], s[30:31]

.LBB0_925:
	s_or_b64 exec, exec, s[24:25]
	ds_read_b32 v8, v12 offset:1820
	v_mov_b64_e32 v[10:11], s[22:23]
	s_and_saveexec_b64 s[24:25], s[44:45]
	s_cbranch_execz .LBB0_927
	v_mov_b64_e32 v[10:11], v[246:247]
	ds_read_b32 v9, v0 offset:1820
	s_lshl_b32 s26, s28, 5
	s_or_b32 s30, s26, 0xe0
	s_waitcnt lgkmcnt(0)
	v_cndmask_b32_e64 v9, v9, -v9, s[40:41]
	v_pk_mul_f32 v[8:9], v[8:9], v[10:11]
	s_nop 0
	v_add_f32_e32 v8, v8, v9
	v_mov_b64_e32 v[10:11], s[30:31]
